# DFT-A GEMM epilogue rewritten: permlane16_swap pairing -> dwordx4 stores (half the store instructions), branch-free mirror variant
# speedup vs baseline: 1.0137x; 1.0012x over previous
; __device__ __forceinline__ unsigned cvt_pk_bf16(float lo, float hi) { unsigned r; asm("v_cvt_pk_bf16_f32 %0, %1, %2" : "=v"(r) : "v"(lo), "v"(hi)); return r; }
;     __device__ __forceinline__ void operator()(const Acc& acc, const Unit& u, int wr, int wc, int fr, int fq) const {
;         const int bk = u.pm >> 2, gr = u.pm & 3, b = bk / 9, ka = bk % 9, ri = u.pn; const bool mir = ka >= 1 && ka <= 7; const unsigned sgn = ri ? 0x80008000u : 0u;
; #pragma unroll
;         for (int ai = 0; ai < 2; ++ai)
; #pragma unroll
;             for (int m = 0; m < 4; ++m) { const int cc = ai * 128 + wr * 64 + m * 16 + 4 * fq; bf16_t* cp = HT + (size_t)gr * 512 + ri * 256 + cc;
; #pragma unroll
;                 for (int bj = 0; bj < 2; ++bj)
; #pragma unroll
;                     for (int n = 0; n < 2; ++n) { const f32x4 a = acc[ai][bj][m][n]; const int kb = bj * 128 + wc * 32 + n * 16 + fr;
;                         u32x2 w; w.x = cvt_pk_bf16(a[0], a[1]); w.y = cvt_pk_bf16(a[2], a[3]); *(u32x2*)(cp + (size_t)(b * 4096 + ka + 16 * kb) * 2048) = w;
;                         if (mir) { u32x2 w2; w2.x = w.x ^ sgn; w2.y = w.y ^ sgn; *(u32x2*)(cp + (size_t)(b * 4096 + (16 - ka) + 16 * (255 - kb)) * 2048) = w2; } } }
.LBB0_1534:
	s_ashr_i32 s9, s8, 2
	s_mul_hi_i32 s25, s9, 0x38e38e39
	s_lshr_b32 s27, s25, 31
	s_ashr_i32 s25, s25, 1
	s_add_i32 s42, s25, s27
	s_mul_i32 s25, s42, 9
	s_sub_i32 s27, s9, s25
	s_add_i32 s58, s27, -1
	s_cmp_lt_u32 s58, 7
	s_cselect_b64 s[40:41], -1, 0
	s_cmp_eq_u32 s57, 0
	s_cselect_b32 s25, 0, 0x80008000
	s_lshl_b32 s44, s57, 8
	s_lshl_b32 s42, s42, 12
	s_lshl_b32 s8, s8, 10
	s_ashr_i32 s45, s44, 31
	s_add_i32 s43, s42, s27
	s_and_b32 s8, s8, 0xc00
	s_add_u32 s57, s18, s8
	s_addc_u32 s59, s19, 0
	s_lshl_b64 s[8:9], s[44:45], 1
	s_add_u32 s8, s57, s8
	s_addc_u32 s9, s59, s9
	v_bfe_u32 v169, v206, 4, 1
	v_mul_u32_u24_e32 v169, 24, v169
	v_lshl_add_u32 v168, v132, 1, v169
	v_add_u32_e32 v169, s43, v147
	v_lshl_add_u32 v160, v169, 12, v168
	v_add_u32_e32 v161, 0x100000, v160
	v_add_u32_e32 v162, 0x800000, v160
	v_add_u32_e32 v163, 0x900000, v160
	s_add_i32 s58, s42, 0x1000
	s_sub_i32 s58, s58, s27
	v_sub_u32_e32 v169, s58, v147
	v_lshl_add_u32 v164, v169, 12, v168
	v_subrev_u32_e32 v165, 0x100000, v164
	v_subrev_u32_e32 v166, 0x800000, v164
	v_subrev_u32_e32 v167, 0x900000, v164
	s_and_b64 vcc, exec, s[40:41]
	s_cbranch_vccz .Lepa_nomirror
	v_cvt_pk_bf16_f32 v172, v124, v125
	v_cvt_pk_bf16_f32 v173, v126, v127
	v_cvt_pk_bf16_f32 v174, v108, v109
	v_cvt_pk_bf16_f32 v175, v110, v111
	s_nop 1
	v_permlane16_swap_b32_e32 v172, v174
	v_permlane16_swap_b32_e32 v173, v175
	global_store_dwordx4 v160, v[172:175], s[8:9]
	v_xor_b32_e32 v180, s25, v172
	v_xor_b32_e32 v181, s25, v173
	v_xor_b32_e32 v182, s25, v174
	v_xor_b32_e32 v183, s25, v175
	global_store_dwordx4 v164, v[180:183], s[8:9]
	v_cvt_pk_bf16_f32 v176, v120, v121
	v_cvt_pk_bf16_f32 v177, v122, v123
	v_cvt_pk_bf16_f32 v178, v104, v105
	v_cvt_pk_bf16_f32 v179, v106, v107
	s_nop 1
	v_permlane16_swap_b32_e32 v176, v178
	v_permlane16_swap_b32_e32 v177, v179
	global_store_dwordx4 v161, v[176:179], s[8:9]
	v_xor_b32_e32 v184, s25, v176
	v_xor_b32_e32 v185, s25, v177
	v_xor_b32_e32 v186, s25, v178
	v_xor_b32_e32 v187, s25, v179
	global_store_dwordx4 v165, v[184:187], s[8:9]
	v_cvt_pk_bf16_f32 v172, v116, v117
	v_cvt_pk_bf16_f32 v173, v118, v119
	v_cvt_pk_bf16_f32 v174, v100, v101
	v_cvt_pk_bf16_f32 v175, v102, v103
	s_nop 1
	v_permlane16_swap_b32_e32 v172, v174
	v_permlane16_swap_b32_e32 v173, v175
	global_store_dwordx4 v162, v[172:175], s[8:9]
	v_xor_b32_e32 v180, s25, v172
	v_xor_b32_e32 v181, s25, v173
	v_xor_b32_e32 v182, s25, v174
	v_xor_b32_e32 v183, s25, v175
	global_store_dwordx4 v166, v[180:183], s[8:9]
	v_cvt_pk_bf16_f32 v176, v112, v113
	v_cvt_pk_bf16_f32 v177, v114, v115
	v_cvt_pk_bf16_f32 v178, v92, v93
	v_cvt_pk_bf16_f32 v179, v94, v95
	s_nop 1
	v_permlane16_swap_b32_e32 v176, v178
	v_permlane16_swap_b32_e32 v177, v179
	global_store_dwordx4 v163, v[176:179], s[8:9]
	v_xor_b32_e32 v184, s25, v176
	v_xor_b32_e32 v185, s25, v177
	v_xor_b32_e32 v186, s25, v178
	v_xor_b32_e32 v187, s25, v179
	global_store_dwordx4 v167, v[184:187], s[8:9]
	v_cvt_pk_bf16_f32 v172, v96, v97
	v_cvt_pk_bf16_f32 v173, v98, v99
	v_cvt_pk_bf16_f32 v174, v80, v81
	v_cvt_pk_bf16_f32 v175, v82, v83
	s_nop 1
	v_permlane16_swap_b32_e32 v172, v174
	v_permlane16_swap_b32_e32 v173, v175
	global_store_dwordx4 v160, v[172:175], s[8:9] offset:64
	v_xor_b32_e32 v180, s25, v172
	v_xor_b32_e32 v181, s25, v173
	v_xor_b32_e32 v182, s25, v174
	v_xor_b32_e32 v183, s25, v175
	global_store_dwordx4 v164, v[180:183], s[8:9] offset:64
	v_cvt_pk_bf16_f32 v176, v88, v89
	v_cvt_pk_bf16_f32 v177, v90, v91
	v_cvt_pk_bf16_f32 v178, v72, v73
	v_cvt_pk_bf16_f32 v179, v74, v75
	s_nop 1
	v_permlane16_swap_b32_e32 v176, v178
	v_permlane16_swap_b32_e32 v177, v179
	global_store_dwordx4 v161, v[176:179], s[8:9] offset:64
	v_xor_b32_e32 v184, s25, v176
	v_xor_b32_e32 v185, s25, v177
	v_xor_b32_e32 v186, s25, v178
	v_xor_b32_e32 v187, s25, v179
	global_store_dwordx4 v165, v[184:187], s[8:9] offset:64
	v_cvt_pk_bf16_f32 v172, v84, v85
	v_cvt_pk_bf16_f32 v173, v86, v87
	v_cvt_pk_bf16_f32 v174, v68, v69
	v_cvt_pk_bf16_f32 v175, v70, v71
	s_nop 1
	v_permlane16_swap_b32_e32 v172, v174
	v_permlane16_swap_b32_e32 v173, v175
	global_store_dwordx4 v162, v[172:175], s[8:9] offset:64
	v_xor_b32_e32 v180, s25, v172
	v_xor_b32_e32 v181, s25, v173
	v_xor_b32_e32 v182, s25, v174
	v_xor_b32_e32 v183, s25, v175
	global_store_dwordx4 v166, v[180:183], s[8:9] offset:64
	v_cvt_pk_bf16_f32 v176, v76, v77
	v_cvt_pk_bf16_f32 v177, v78, v79
	v_cvt_pk_bf16_f32 v178, v64, v65
	v_cvt_pk_bf16_f32 v179, v66, v67
	s_nop 1
	v_permlane16_swap_b32_e32 v176, v178
	v_permlane16_swap_b32_e32 v177, v179
	global_store_dwordx4 v163, v[176:179], s[8:9] offset:64
	v_xor_b32_e32 v184, s25, v176
	v_xor_b32_e32 v185, s25, v177
	v_xor_b32_e32 v186, s25, v178
	v_xor_b32_e32 v187, s25, v179
	global_store_dwordx4 v167, v[184:187], s[8:9] offset:64
	v_cvt_pk_bf16_f32 v172, v60, v61
	v_cvt_pk_bf16_f32 v173, v62, v63
	v_cvt_pk_bf16_f32 v174, v48, v49
	v_cvt_pk_bf16_f32 v175, v50, v51
	s_nop 1
	v_permlane16_swap_b32_e32 v172, v174
	v_permlane16_swap_b32_e32 v173, v175
	global_store_dwordx4 v160, v[172:175], s[8:9] offset:256
	v_xor_b32_e32 v180, s25, v172
	v_xor_b32_e32 v181, s25, v173
	v_xor_b32_e32 v182, s25, v174
	v_xor_b32_e32 v183, s25, v175
	global_store_dwordx4 v164, v[180:183], s[8:9] offset:256
	v_cvt_pk_bf16_f32 v176, v56, v57
	v_cvt_pk_bf16_f32 v177, v58, v59
	v_cvt_pk_bf16_f32 v178, v40, v41
	v_cvt_pk_bf16_f32 v179, v42, v43
	s_nop 1
	v_permlane16_swap_b32_e32 v176, v178
	v_permlane16_swap_b32_e32 v177, v179
	global_store_dwordx4 v161, v[176:179], s[8:9] offset:256
	v_xor_b32_e32 v184, s25, v176
	v_xor_b32_e32 v185, s25, v177
	v_xor_b32_e32 v186, s25, v178
	v_xor_b32_e32 v187, s25, v179
; __device__ __forceinline__ unsigned cvt_pk_bf16(float lo, float hi) { unsigned r; asm("v_cvt_pk_bf16_f32 %0, %1, %2" : "=v"(r) : "v"(lo), "v"(hi)); return r; }
;     __device__ __forceinline__ void operator()(const Acc& acc, const Unit& u, int wr, int wc, int fr, int fq) const {
;     ...
;             for (int m = 0; m < 4; ++m) { const int cc = ai * 128 + wr * 64 + m * 16 + 4 * fq; bf16_t* cp = HT + (size_t)gr * 512 + ri * 256 + cc;
; #pragma unroll
;                 for (int bj = 0; bj < 2; ++bj)
; #pragma unroll
;                     for (int n = 0; n < 2; ++n) { const f32x4 a = acc[ai][bj][m][n]; const int kb = bj * 128 + wc * 32 + n * 16 + fr;
;                         u32x2 w; w.x = cvt_pk_bf16(a[0], a[1]); w.y = cvt_pk_bf16(a[2], a[3]); *(u32x2*)(cp + (size_t)(b * 4096 + ka + 16 * kb) * 2048) = w;
;                         if (mir) { u32x2 w2; w2.x = w.x ^ sgn; w2.y = w.y ^ sgn; *(u32x2*)(cp + (size_t)(b * 4096 + (16 - ka) + 16 * (255 - kb)) * 2048) = w2; } } }
	global_store_dwordx4 v165, v[184:187], s[8:9] offset:256
	v_cvt_pk_bf16_f32 v172, v52, v53
	v_cvt_pk_bf16_f32 v173, v54, v55
	v_cvt_pk_bf16_f32 v174, v36, v37
	v_cvt_pk_bf16_f32 v175, v38, v39
	s_nop 1
	v_permlane16_swap_b32_e32 v172, v174
	v_permlane16_swap_b32_e32 v173, v175
	global_store_dwordx4 v162, v[172:175], s[8:9] offset:256
	v_xor_b32_e32 v180, s25, v172
	v_xor_b32_e32 v181, s25, v173
	v_xor_b32_e32 v182, s25, v174
	v_xor_b32_e32 v183, s25, v175
	global_store_dwordx4 v166, v[180:183], s[8:9] offset:256
	v_cvt_pk_bf16_f32 v176, v44, v45
	v_cvt_pk_bf16_f32 v177, v46, v47
	v_cvt_pk_bf16_f32 v178, v28, v29
	v_cvt_pk_bf16_f32 v179, v30, v31
	s_nop 1
	v_permlane16_swap_b32_e32 v176, v178
	v_permlane16_swap_b32_e32 v177, v179
	global_store_dwordx4 v163, v[176:179], s[8:9] offset:256
	v_xor_b32_e32 v184, s25, v176
	v_xor_b32_e32 v185, s25, v177
	v_xor_b32_e32 v186, s25, v178
	v_xor_b32_e32 v187, s25, v179
	global_store_dwordx4 v167, v[184:187], s[8:9] offset:256
	v_cvt_pk_bf16_f32 v172, v32, v33
	v_cvt_pk_bf16_f32 v173, v34, v35
	v_cvt_pk_bf16_f32 v174, v16, v17
	v_cvt_pk_bf16_f32 v175, v18, v19
	s_nop 1
	v_permlane16_swap_b32_e32 v172, v174
	v_permlane16_swap_b32_e32 v173, v175
	global_store_dwordx4 v160, v[172:175], s[8:9] offset:320
	v_xor_b32_e32 v180, s25, v172
	v_xor_b32_e32 v181, s25, v173
	v_xor_b32_e32 v182, s25, v174
	v_xor_b32_e32 v183, s25, v175
	global_store_dwordx4 v164, v[180:183], s[8:9] offset:320
	v_cvt_pk_bf16_f32 v176, v24, v25
	v_cvt_pk_bf16_f32 v177, v26, v27
	v_cvt_pk_bf16_f32 v178, v8, v9
	v_cvt_pk_bf16_f32 v179, v10, v11
	s_nop 1
	v_permlane16_swap_b32_e32 v176, v178
	v_permlane16_swap_b32_e32 v177, v179
	global_store_dwordx4 v161, v[176:179], s[8:9] offset:320
	v_xor_b32_e32 v184, s25, v176
	v_xor_b32_e32 v185, s25, v177
	v_xor_b32_e32 v186, s25, v178
	v_xor_b32_e32 v187, s25, v179
	global_store_dwordx4 v165, v[184:187], s[8:9] offset:320
	v_cvt_pk_bf16_f32 v172, v20, v21
	v_cvt_pk_bf16_f32 v173, v22, v23
	v_cvt_pk_bf16_f32 v174, v4, v5
	v_cvt_pk_bf16_f32 v175, v6, v7
	s_nop 1
	v_permlane16_swap_b32_e32 v172, v174
	v_permlane16_swap_b32_e32 v173, v175
	global_store_dwordx4 v162, v[172:175], s[8:9] offset:320
	v_xor_b32_e32 v180, s25, v172
	v_xor_b32_e32 v181, s25, v173
	v_xor_b32_e32 v182, s25, v174
	v_xor_b32_e32 v183, s25, v175
	global_store_dwordx4 v166, v[180:183], s[8:9] offset:320
	v_cvt_pk_bf16_f32 v176, v12, v13
	v_cvt_pk_bf16_f32 v177, v14, v15
	v_cvt_pk_bf16_f32 v178, v0, v1
	v_cvt_pk_bf16_f32 v179, v2, v3
	s_nop 1
	v_permlane16_swap_b32_e32 v176, v178
	v_permlane16_swap_b32_e32 v177, v179
	global_store_dwordx4 v163, v[176:179], s[8:9] offset:320
	v_xor_b32_e32 v184, s25, v176
	v_xor_b32_e32 v185, s25, v177
	v_xor_b32_e32 v186, s25, v178
	v_xor_b32_e32 v187, s25, v179
	global_store_dwordx4 v167, v[184:187], s[8:9] offset:320
	s_branch .LBB0_1598
; __device__ __forceinline__ unsigned cvt_pk_bf16(float lo, float hi) { unsigned r; asm("v_cvt_pk_bf16_f32 %0, %1, %2" : "=v"(r) : "v"(lo), "v"(hi)); return r; }
;     __device__ __forceinline__ void operator()(const Acc& acc, const Unit& u, int wr, int wc, int fr, int fq) const {
;     ...
;             for (int m = 0; m < 4; ++m) { const int cc = ai * 128 + wr * 64 + m * 16 + 4 * fq; bf16_t* cp = HT + (size_t)gr * 512 + ri * 256 + cc;
; #pragma unroll
;                 for (int bj = 0; bj < 2; ++bj)
; #pragma unroll
;                     for (int n = 0; n < 2; ++n) { const f32x4 a = acc[ai][bj][m][n]; const int kb = bj * 128 + wc * 32 + n * 16 + fr;
;                         u32x2 w; w.x = cvt_pk_bf16(a[0], a[1]); w.y = cvt_pk_bf16(a[2], a[3]); *(u32x2*)(cp + (size_t)(b * 4096 + ka + 16 * kb) * 2048) = w;
;                         if (mir) { u32x2 w2; w2.x = w.x ^ sgn; w2.y = w.y ^ sgn; *(u32x2*)(cp + (size_t)(b * 4096 + (16 - ka) + 16 * (255 - kb)) * 2048) = w2; } } }
.Lepa_nomirror:
	v_cvt_pk_bf16_f32 v172, v124, v125
	v_cvt_pk_bf16_f32 v173, v126, v127
	v_cvt_pk_bf16_f32 v174, v108, v109
	v_cvt_pk_bf16_f32 v175, v110, v111
	s_nop 1
	v_permlane16_swap_b32_e32 v172, v174
	v_permlane16_swap_b32_e32 v173, v175
	global_store_dwordx4 v160, v[172:175], s[8:9]
	v_cvt_pk_bf16_f32 v176, v120, v121
	v_cvt_pk_bf16_f32 v177, v122, v123
	v_cvt_pk_bf16_f32 v178, v104, v105
	v_cvt_pk_bf16_f32 v179, v106, v107
	s_nop 1
	v_permlane16_swap_b32_e32 v176, v178
	v_permlane16_swap_b32_e32 v177, v179
	global_store_dwordx4 v161, v[176:179], s[8:9]
	v_cvt_pk_bf16_f32 v172, v116, v117
	v_cvt_pk_bf16_f32 v173, v118, v119
	v_cvt_pk_bf16_f32 v174, v100, v101
	v_cvt_pk_bf16_f32 v175, v102, v103
	s_nop 1
	v_permlane16_swap_b32_e32 v172, v174
	v_permlane16_swap_b32_e32 v173, v175
	global_store_dwordx4 v162, v[172:175], s[8:9]
	v_cvt_pk_bf16_f32 v176, v112, v113
	v_cvt_pk_bf16_f32 v177, v114, v115
	v_cvt_pk_bf16_f32 v178, v92, v93
	v_cvt_pk_bf16_f32 v179, v94, v95
	s_nop 1
	v_permlane16_swap_b32_e32 v176, v178
	v_permlane16_swap_b32_e32 v177, v179
	global_store_dwordx4 v163, v[176:179], s[8:9]
	v_cvt_pk_bf16_f32 v172, v96, v97
	v_cvt_pk_bf16_f32 v173, v98, v99
	v_cvt_pk_bf16_f32 v174, v80, v81
	v_cvt_pk_bf16_f32 v175, v82, v83
	s_nop 1
	v_permlane16_swap_b32_e32 v172, v174
	v_permlane16_swap_b32_e32 v173, v175
	global_store_dwordx4 v160, v[172:175], s[8:9] offset:64
	v_cvt_pk_bf16_f32 v176, v88, v89
	v_cvt_pk_bf16_f32 v177, v90, v91
	v_cvt_pk_bf16_f32 v178, v72, v73
	v_cvt_pk_bf16_f32 v179, v74, v75
	s_nop 1
	v_permlane16_swap_b32_e32 v176, v178
	v_permlane16_swap_b32_e32 v177, v179
	global_store_dwordx4 v161, v[176:179], s[8:9] offset:64
	v_cvt_pk_bf16_f32 v172, v84, v85
	v_cvt_pk_bf16_f32 v173, v86, v87
	v_cvt_pk_bf16_f32 v174, v68, v69
	v_cvt_pk_bf16_f32 v175, v70, v71
	s_nop 1
	v_permlane16_swap_b32_e32 v172, v174
	v_permlane16_swap_b32_e32 v173, v175
	global_store_dwordx4 v162, v[172:175], s[8:9] offset:64
	v_cvt_pk_bf16_f32 v176, v76, v77
	v_cvt_pk_bf16_f32 v177, v78, v79
	v_cvt_pk_bf16_f32 v178, v64, v65
	v_cvt_pk_bf16_f32 v179, v66, v67
	s_nop 1
	v_permlane16_swap_b32_e32 v176, v178
	v_permlane16_swap_b32_e32 v177, v179
	global_store_dwordx4 v163, v[176:179], s[8:9] offset:64
	v_cvt_pk_bf16_f32 v172, v60, v61
	v_cvt_pk_bf16_f32 v173, v62, v63
	v_cvt_pk_bf16_f32 v174, v48, v49
	v_cvt_pk_bf16_f32 v175, v50, v51
	s_nop 1
	v_permlane16_swap_b32_e32 v172, v174
	v_permlane16_swap_b32_e32 v173, v175
	global_store_dwordx4 v160, v[172:175], s[8:9] offset:256
	v_cvt_pk_bf16_f32 v176, v56, v57
	v_cvt_pk_bf16_f32 v177, v58, v59
	v_cvt_pk_bf16_f32 v178, v40, v41
	v_cvt_pk_bf16_f32 v179, v42, v43
	s_nop 1
	v_permlane16_swap_b32_e32 v176, v178
	v_permlane16_swap_b32_e32 v177, v179
	global_store_dwordx4 v161, v[176:179], s[8:9] offset:256
	v_cvt_pk_bf16_f32 v172, v52, v53
	v_cvt_pk_bf16_f32 v173, v54, v55
	v_cvt_pk_bf16_f32 v174, v36, v37
	v_cvt_pk_bf16_f32 v175, v38, v39
	s_nop 1
	v_permlane16_swap_b32_e32 v172, v174
	v_permlane16_swap_b32_e32 v173, v175
	global_store_dwordx4 v162, v[172:175], s[8:9] offset:256
	v_cvt_pk_bf16_f32 v176, v44, v45
	v_cvt_pk_bf16_f32 v177, v46, v47
	v_cvt_pk_bf16_f32 v178, v28, v29
	v_cvt_pk_bf16_f32 v179, v30, v31
	s_nop 1
	v_permlane16_swap_b32_e32 v176, v178
	v_permlane16_swap_b32_e32 v177, v179
	global_store_dwordx4 v163, v[176:179], s[8:9] offset:256
	v_cvt_pk_bf16_f32 v172, v32, v33
	v_cvt_pk_bf16_f32 v173, v34, v35
	v_cvt_pk_bf16_f32 v174, v16, v17
	v_cvt_pk_bf16_f32 v175, v18, v19
	s_nop 1
	v_permlane16_swap_b32_e32 v172, v174
	v_permlane16_swap_b32_e32 v173, v175
	global_store_dwordx4 v160, v[172:175], s[8:9] offset:320
	v_cvt_pk_bf16_f32 v176, v24, v25
	v_cvt_pk_bf16_f32 v177, v26, v27
	v_cvt_pk_bf16_f32 v178, v8, v9
	v_cvt_pk_bf16_f32 v179, v10, v11
	s_nop 1
	v_permlane16_swap_b32_e32 v176, v178
	v_permlane16_swap_b32_e32 v177, v179
	global_store_dwordx4 v161, v[176:179], s[8:9] offset:320
	v_cvt_pk_bf16_f32 v172, v20, v21
	v_cvt_pk_bf16_f32 v173, v22, v23
	v_cvt_pk_bf16_f32 v174, v4, v5
	v_cvt_pk_bf16_f32 v175, v6, v7
	s_nop 1
	v_permlane16_swap_b32_e32 v172, v174
	v_permlane16_swap_b32_e32 v173, v175
	global_store_dwordx4 v162, v[172:175], s[8:9] offset:320
	v_cvt_pk_bf16_f32 v176, v12, v13
	v_cvt_pk_bf16_f32 v177, v14, v15
	v_cvt_pk_bf16_f32 v178, v0, v1
	v_cvt_pk_bf16_f32 v179, v2, v3
	s_nop 1
	v_permlane16_swap_b32_e32 v176, v178
	v_permlane16_swap_b32_e32 v177, v179
	global_store_dwordx4 v163, v[176:179], s[8:9] offset:320
